# P1 and P8 unit order regrouped to 4 row tiles x 8 column tiles per XCD round; attention max tree shortened; skinny k-step loads batched
# speedup vs baseline: 1.0112x; 1.0027x over previous
;     __host__ __device__ bool next(int i, Unit& u) const {
;     ...
;         int wgid = (int)L; { const int q = nwg / NXCD, r = nwg % NXCD, xcd = wgid % NXCD, off = wgid / NXCD; wgid = (xcd < r ? xcd * (q + 1) : r * (q + 1) + (xcd - r) * q) + off; }
;         const int nig = WGM * nN, gid = wgid / nig, fm = gid * WGM, gsz = (nM - fm) < WGM ? (nM - fm) : WGM;
;         u.pm = fm + ((wgid % nig) % gsz); u.pn = (wgid % nig) / gsz; return true;
.LBB0_1181:
	s_mov_b64 s[4:5], s[0:1]
	s_mov_b64 s[8:9], s[0:1]
	s_mov_b64 s[6:7], s[0:1]
	s_mov_b64 s[10:11], s[0:1]
	s_mov_b64 s[12:13], s[0:1]
	s_mov_b64 s[18:19], s[0:1]
	s_mov_b64 s[20:21], s[0:1]
	s_mov_b64 s[16:17], s[0:1]
	s_mov_b64 s[22:23], s[0:1]
	v_mov_b32_e32 v10, v218
	s_cmpk_lt_i32 s2, 0xb00
	s_cselect_b64 s[24:25], -1, 0
	s_cmpk_gt_i32 s2, 0xaff
	v_readfirstlane_b32 s28, v10
	s_cbranch_scc1 .LBB0_1183
	s_ashr_i32 s26, s2, 31
	s_lshr_b32 s26, s26, 29
	s_add_i32 s26, s2, s26
	s_ashr_i32 s27, s26, 3
	s_and_b32 s26, s26, -8
	s_sub_i32 s26, s2, s26
	s_cmp_lt_i32 s26, 0
	s_movk_i32 s29, 0x161
	s_cselect_b32 s29, s29, 0x160
	s_mul_i32 s26, s26, s29
	s_add_i32 s26, s26, s27
	s_mul_hi_i32 s27, s26, 0x2e8ba2e9
	s_lshr_b32 s29, s27, 31
	s_ashr_i32 s27, s27, 4
	s_add_i32 s27, s27, s29
	s_lshl_b32 s29, s27, 2
	s_mul_i32 s27, s27, 0x58
	s_sub_i32 s26, s26, s27
	s_and_b32 s27, s26, 3
	s_add_i32 s54, s29, s27
	s_lshr_b32 s56, s26, 2
	s_mov_b32 s30, 0

;     __host__ __device__ bool next(int i, Unit& u) const {
;     ...
;         int wgid = (int)L; { const int q = nwg / NXCD, r = nwg % NXCD, xcd = wgid % NXCD, off = wgid / NXCD; wgid = (xcd < r ? xcd * (q + 1) : r * (q + 1) + (xcd - r) * q) + off; }
;         const int nig = WGM * nN, gid = wgid / nig, fm = gid * WGM, gsz = (nM - fm) < WGM ? (nM - fm) : WGM;
;         u.pm = fm + ((wgid % nig) % gsz); u.pn = (wgid % nig) / gsz; return true;
.LBB0_1189:
	s_add_i32 s79, s79, 1
	s_mul_i32 s12, s79, s88
	s_mul_hi_u32 s13, s79, s3
	s_add_i32 s13, s13, s12
	s_mul_i32 s12, s79, s3
	s_add_u32 s50, s12, s2
	s_addc_u32 s51, s13, s89
	v_cmp_gt_i64_e32 vcc, s[50:51], v[196:197]
	v_cmp_lt_i64_e64 s[12:13], s[50:51], v[194:195]
	s_cbranch_vccnz .LBB0_1191
	s_ashr_i32 s33, s50, 31
	s_lshr_b32 s33, s33, 29
	s_add_i32 s33, s50, s33
	s_ashr_i32 s38, s33, 3
	s_and_b32 s33, s33, -8
	s_sub_i32 s33, s50, s33
	s_cmp_lt_i32 s33, 0
	s_movk_i32 s39, 0x161
	s_cselect_b32 s39, s39, 0x160
	s_mul_i32 s33, s33, s39
	s_add_i32 s33, s33, s38
	s_mul_hi_i32 s38, s33, 0x2e8ba2e9
	s_lshr_b32 s39, s38, 31
	s_ashr_i32 s38, s38, 4
	s_add_i32 s38, s38, s39
	s_lshl_b32 s39, s38, 2
	s_sub_i32 s46, 0x80, s39
	s_min_i32 s47, s46, 4
	s_abs_i32 s46, s47
	v_cvt_f32_u32_e32 v0, s46
	s_sub_i32 s49, 0, s46
	s_mul_i32 s38, s38, 0x58
	s_sub_i32 s33, s33, s38
	v_rcp_iflag_f32_e32 v0, v0
	s_abs_i32 s38, s33
	s_xor_b32 s48, s33, s47
	s_ashr_i32 s48, s48, 31
	v_mul_f32_e32 v0, 0x4f7ffffe, v0
	v_cvt_u32_f32_e32 v0, v0
	s_nop 0
	v_readfirstlane_b32 s50, v0
	s_mul_i32 s49, s49, s50
	s_mul_hi_u32 s49, s50, s49
	s_add_i32 s50, s50, s49
	s_mul_hi_u32 s49, s38, s50
	s_mul_i32 s50, s49, s46
	s_sub_i32 s38, s38, s50
	s_add_i32 s51, s49, 1
	s_sub_i32 s50, s38, s46
	s_cmp_ge_u32 s38, s46
	s_cselect_b32 s49, s51, s49
	s_cselect_b32 s38, s50, s38
	s_add_i32 s50, s49, 1
	s_cmp_ge_u32 s38, s46
	s_cselect_b32 s38, s50, s49
	s_xor_b32 s38, s38, s48
	s_sub_i32 s46, s38, s48
	s_mul_i32 s38, s46, s47
	s_sub_i32 s33, s33, s38
	s_add_i32 s48, s39, s33
